# added batched-load fast path for the in-projection weight transpose (MAPIN) on top of previous edits
# speedup vs baseline: 1.0214x; 1.0054x over previous
; #define LAS __attribute__((address_space(3)))
; __device__ __forceinline__ int map_in_col(int nd) {
;     if (nd < QOFF) return nd;
;     if (nd < DTOFF) return nd + 24;
;     if (nd < DTOFF + 24) return nd - DTOFF + QOFF;
;     return -1;
; }
; template <bool MAPIN>
; __device__ __forceinline__ void transpose_item(const float* W, const float* gk, int K, int Nsrc, int nblk, bf16_t* WT, LAS float* scr, int item, int lane) {
;     const int kb = item / nblk, nb = item % nblk, k0 = 64 * kb, n0 = 32 * nb;
;     const int nd = n0 + (lane & 31); const int ns = MAPIN ? map_in_col(nd) : nd;
; #pragma unroll 8
;     for (int i = 0; i < 32; ++i) { const int kk = 2 * i + (lane >> 5); const float gg = gk ? gk[k0 + kk] : 1.f; scr[kk * 33 + (lane & 31)] = (ns >= 0) ? W[(size_t)(k0 + kk) * Nsrc + ns] * gg : 0.f; }
;     asm volatile("s_waitcnt lgkmcnt(0)" ::: "memory");
; __global__ void __launch_bounds__(512, 2) hybrid_fwd(Params P0) {
;     ...
;                 if (q < I_IN) { transpose_item<true>(P.in[I_WIN] + (size_t)L * DM * IN_COLS, P.in[I_NMIXG] + L * DM, DM, IN_COLS, 176, (bf16_t*)(P.ws + WS_WIN), scr, q, lane); continue; } q -= I_IN;
.LBB0_475:
	s_or_b64 exec, exec, s[0:1]
	s_load_dwordx4 s[4:7], s[64:65], 0x20
	s_lshl_b32 s18, s18, 6
	v_or_b32_e32 v3, s18, v48
	v_lshlrev_b64 v[34:35], 2, v[192:193]
	v_mad_i64_i32 v[18:19], s[30:31], v3, s56, v[34:35]
	v_or_b32_e32 v3, s18, v49
	v_mad_i64_i32 v[22:23], s[30:31], v3, s56, v[34:35]
	v_or_b32_e32 v3, s18, v50
	v_mad_i64_i32 v[24:25], s[30:31], v3, s56, v[34:35]
	v_or_b32_e32 v3, s18, v51
	s_waitcnt lgkmcnt(0)
	s_cmp_lg_u64 s[4:5], 0
	v_mad_i64_i32 v[26:27], s[30:31], v3, s56, v[34:35]
	v_or_b32_e32 v3, s18, v52
	s_cselect_b64 s[22:23], -1, 0
	s_ashr_i32 s19, s18, 31
	v_mad_i64_i32 v[28:29], s[30:31], v3, s56, v[34:35]
	v_or_b32_e32 v3, s18, v53
	v_mov_b32_e32 v37, s19
	v_or_b32_e32 v36, s18, v0
	s_add_u32 s6, s6, s25
	v_mad_i64_i32 v[30:31], s[30:31], v3, s56, v[34:35]
	v_or_b32_e32 v3, s18, v54
	s_addc_u32 s7, s7, s24
	v_lshl_add_u64 v[20:21], v[36:37], 2, s[4:5]
	v_mad_i64_i32 v[32:33], s[30:31], v3, s56, v[34:35]
	v_ashrrev_i32_e32 v37, 31, v36
	v_mad_i64_i32 v[34:35], s[30:31], v36, s56, v[34:35]
	s_mov_b64 s[20:21], 0
	v_cmp_lt_i32_e64 s[0:1], -1, v192
	v_lshl_add_u64 v[18:19], s[6:7], 0, v[18:19]
	v_lshl_add_u64 v[22:23], s[6:7], 0, v[22:23]
	v_lshl_add_u64 v[24:25], s[6:7], 0, v[24:25]
	v_lshl_add_u64 v[26:27], s[6:7], 0, v[26:27]
	v_lshl_add_u64 v[28:29], s[6:7], 0, v[28:29]
	v_lshl_add_u64 v[30:31], s[6:7], 0, v[30:31]
	v_lshl_add_u64 v[32:33], s[6:7], 0, v[32:33]
	v_lshl_add_u64 v[34:35], s[6:7], 0, v[34:35]
	v_lshl_add_u64 v[36:37], v[36:37], 2, s[4:5]
	v_mov_b32_e32 v3, v47
	s_and_b64 vcc, exec, s[22:23]
	s_cbranch_vccnz .Ltr477_fast
	s_branch .LBB0_477
.Ltr477_fast:
	v_lshl_add_u64 v[56:57], v[36:37], 0, s[16:17]
	global_load_dword v70, v[56:57], off
	v_lshl_add_u64 v[58:59], v[20:21], 0, s[16:17]
	global_load_dword v71, v[58:59], off offset:8
	global_load_dword v72, v[58:59], off offset:16
	global_load_dword v73, v[58:59], off offset:24
	global_load_dword v74, v[58:59], off offset:32
	global_load_dword v75, v[58:59], off offset:40
	global_load_dword v76, v[58:59], off offset:48
	global_load_dword v77, v[58:59], off offset:56
	v_mov_b32_e32 v78, 0
	v_mov_b32_e32 v79, 0
	v_mov_b32_e32 v80, 0
	v_mov_b32_e32 v81, 0
	v_mov_b32_e32 v82, 0
	v_mov_b32_e32 v83, 0
	v_mov_b32_e32 v84, 0
	v_mov_b32_e32 v85, 0
	s_and_saveexec_b64 s[6:7], s[0:1]
	v_lshl_add_u64 v[60:61], v[34:35], 0, s[20:21]
	global_load_dword v78, v[60:61], off
	v_lshl_add_u64 v[62:63], v[32:33], 0, s[20:21]
	global_load_dword v79, v[62:63], off
	v_lshl_add_u64 v[60:61], v[30:31], 0, s[20:21]
	global_load_dword v80, v[60:61], off
	v_lshl_add_u64 v[62:63], v[28:29], 0, s[20:21]
	global_load_dword v81, v[62:63], off
	v_lshl_add_u64 v[60:61], v[26:27], 0, s[20:21]
	global_load_dword v82, v[60:61], off
	v_lshl_add_u64 v[62:63], v[24:25], 0, s[20:21]
	global_load_dword v83, v[62:63], off
	v_lshl_add_u64 v[60:61], v[22:23], 0, s[20:21]
	global_load_dword v84, v[60:61], off
	v_lshl_add_u64 v[62:63], v[18:19], 0, s[20:21]
	global_load_dword v85, v[62:63], off
	s_mov_b64 exec, s[6:7]
	s_add_u32 s20, s20, 0x54600
	s_addc_u32 s21, s21, 0
	v_lshl_add_u64 v[20:21], v[20:21], 0, 64
	v_lshl_add_u64 v[36:37], v[36:37], 0, 64
	s_waitcnt vmcnt(7)
	v_mul_f32_e32 v70, v70, v78
	v_cndmask_b32_e64 v70, 0, v70, s[0:1]
	ds_write_b32 v3, v70
	s_waitcnt vmcnt(6)
	v_mul_f32_e32 v71, v71, v79
	v_cndmask_b32_e64 v71, 0, v71, s[0:1]
	ds_write_b32 v3, v71 offset:264
	s_waitcnt vmcnt(5)
	v_mul_f32_e32 v72, v72, v80
	v_cndmask_b32_e64 v72, 0, v72, s[0:1]
	ds_write_b32 v3, v72 offset:528
	s_waitcnt vmcnt(4)
	v_mul_f32_e32 v73, v73, v81
	v_cndmask_b32_e64 v73, 0, v73, s[0:1]
	ds_write_b32 v3, v73 offset:792
	s_waitcnt vmcnt(3)
	v_mul_f32_e32 v74, v74, v82
	v_cndmask_b32_e64 v74, 0, v74, s[0:1]
	ds_write_b32 v3, v74 offset:1056
	s_waitcnt vmcnt(2)
	v_mul_f32_e32 v75, v75, v83
	v_cndmask_b32_e64 v75, 0, v75, s[0:1]
	ds_write_b32 v3, v75 offset:1320
	s_waitcnt vmcnt(1)
	v_mul_f32_e32 v76, v76, v84
	v_cndmask_b32_e64 v76, 0, v76, s[0:1]
	ds_write_b32 v3, v76 offset:1584
	s_waitcnt vmcnt(0)
	v_mul_f32_e32 v77, v77, v85
	v_cndmask_b32_e64 v77, 0, v77, s[0:1]
	ds_write_b32 v3, v77 offset:1848
	v_add_u32_e32 v3, 0x840, v3
	s_cmp_lg_u32 s20, 0x151800
	s_cbranch_scc1 .Ltr477_fast
	s_branch .LBB0_406
